# gMLP chunk loop: gain and gelu(u) loads issued early (5 waits per group to 3) + chunk workgroups take rows [0,4096)
# speedup vs baseline: 1.0024x; 1.0024x over previous
; __device__ __forceinline__ bf16_t f2bf(float f) { return (bf16_t)(pkbf(f, 0.f) & 0xffffu); }
; __device__ __forceinline__ void gmlp_unit(const TI ti, CArgs& a, int l, int u, unsigned char* ldsg) {
;     ...
;     for (int g = 0; g < 8; ++g) {
;         {
;             const int s = tid & 127, cc = tid >> 7; const float rs = rstd[s]; const bf16_t* p = GV + (R0 + s) * 1024 + g * 128 + cc * 32;
; #pragma unroll
;             for (int q = 0; q < 4; ++q) {
;                 f32x4 x0, x1; unpack8(*(const u32x4*)(p + 8 * q), x0, x1);
;                 const float* gp = gvg + g * 128 + cc * 32 + 8 * q; const int c0 = cc * 32 + 8 * q;
;                 VNT[(c0 + 0) * 136 + s] = f2bf(x0.x * rs * gp[0]); VNT[(c0 + 1) * 136 + s] = f2bf(x0.y * rs * gp[1]);
;                 VNT[(c0 + 2) * 136 + s] = f2bf(x0.z * rs * gp[2]); VNT[(c0 + 3) * 136 + s] = f2bf(x0.w * rs * gp[3]);
;                 VNT[(c0 + 4) * 136 + s] = f2bf(x1.x * rs * gp[4]); VNT[(c0 + 5) * 136 + s] = f2bf(x1.y * rs * gp[5]);
;                 VNT[(c0 + 6) * 136 + s] = f2bf(x1.z * rs * gp[6]); VNT[(c0 + 7) * 136 + s] = f2bf(x1.w * rs * gp[7]);
;             }
;         }
;         __syncthreads();
.LBB0_447:
	global_load_dwordx4 v[90:93], v[144:145], off offset:-256
	global_load_dwordx4 v[94:97], v[144:145], off offset:-240
	global_load_dwordx4 v[98:101], v[144:145], off offset:-192
	global_load_dwordx4 v[162:165], v[144:145], off offset:-176
	global_load_dwordx4 v[198:201], v[144:145], off offset:-128
	global_load_dwordx4 v[202:205], v[144:145], off offset:-112
	global_load_dwordx4 v[206:209], v[144:145], off offset:-64
	global_load_dwordx4 v[210:213], v[144:145], off offset:-48
	v_lshl_add_u64 v[14:15], v[146:147], 0, s[42:43]
	ds_read_b32 v0, v156
	global_load_dwordx4 v[2:5], v[14:15], off offset:16
	global_load_dwordx4 v[6:9], v[14:15], off
	global_load_dwordx4 v[10:13], v[14:15], off offset:-16
	s_nop 0
	global_load_dwordx4 v[14:17], v[14:15], off offset:-32
	v_lshl_add_u64 v[30:31], v[102:103], 0, s[46:47]
	global_load_dwordx4 v[222:225], v[30:31], off offset:48
	global_load_dwordx4 v[226:229], v[30:31], off offset:32
	global_load_dwordx4 v[230:233], v[30:31], off offset:16
	global_load_dwordx4 v[234:237], v[30:31], off
	global_load_dwordx4 v[238:241], v[30:31], off offset:112
	global_load_dwordx4 v[242:245], v[30:31], off offset:96
	global_load_dwordx4 v[246:249], v[30:31], off offset:80
	global_load_dwordx4 v[250:253], v[30:31], off offset:64
	v_lshl_add_u64 v[150:151], v[130:131], 0, s[42:43]
	v_lshl_add_u64 v[154:155], v[134:135], 0, s[42:43]
	v_lshl_add_u64 v[168:169], v[138:139], 0, s[42:43]
	s_mov_b32 s3, 0x5e01000
	s_mov_b64 s[4:5], 0x10000
	v_lshl_add_u64 v[146:147], v[146:147], 0, s[24:25]
	v_lshl_add_u64 v[138:139], v[138:139], 0, s[24:25]
	v_lshl_add_u64 v[134:135], v[134:135], 0, s[24:25]
	v_lshl_add_u64 v[130:131], v[130:131], 0, s[24:25]
	s_waitcnt vmcnt(0)
	v_lshlrev_b32_e32 v18, 16, v14
	v_and_b32_e32 v32, 0xffff0000, v14
	v_lshlrev_b32_e32 v33, 16, v15
	v_and_b32_e32 v34, 0xffff0000, v15
	v_lshlrev_b32_e32 v35, 16, v16
	v_and_b32_e32 v36, 0xffff0000, v16
	v_lshlrev_b32_e32 v37, 16, v17
	v_and_b32_e32 v38, 0xffff0000, v17
	s_waitcnt lgkmcnt(0)
	v_mul_f32_e32 v39, v0, v18
	v_mul_f32_e32 v26, v234, v39
	v_cvt_pk_bf16_f32 v26, v26, s0
	ds_write_b16 v158, v26 offset:512
	v_mul_f32_e32 v26, v0, v32
	v_mul_f32_e32 v26, v235, v26
	v_cvt_pk_bf16_f32 v26, v26, s0
	ds_write_b16 v159, v26 offset:784
	v_mul_f32_e32 v26, v0, v33
	v_mul_f32_e32 v26, v26, v236
	v_cvt_pk_bf16_f32 v26, v26, s0
	ds_write_b16 v159, v26 offset:1056
	v_mul_f32_e32 v26, v0, v34
	v_mul_f32_e32 v26, v26, v237
	v_cvt_pk_bf16_f32 v26, v26, s0
	ds_write_b16 v159, v26 offset:1328
	v_mul_f32_e32 v26, v0, v35
	v_mul_f32_e32 v22, v26, v230
	v_cvt_pk_bf16_f32 v22, v22, s0
	ds_write_b16 v159, v22 offset:1600
	v_mul_f32_e32 v22, v0, v36
	v_mul_f32_e32 v22, v22, v231
	v_cvt_pk_bf16_f32 v22, v22, s0
	ds_write_b16 v159, v22 offset:1872
	v_mul_f32_e32 v22, v0, v37
	v_mul_f32_e32 v22, v22, v232
	v_cvt_pk_bf16_f32 v22, v22, s0
	ds_write_b16 v159, v22 offset:2144
	v_mul_f32_e32 v22, v0, v38
	v_mul_f32_e32 v22, v22, v233
	v_cvt_pk_bf16_f32 v22, v22, s0
	ds_write_b16 v159, v22 offset:2416
	v_lshlrev_b32_e32 v22, 16, v10
	v_and_b32_e32 v10, 0xffff0000, v10
	v_mul_f32_e32 v22, v0, v22
	v_mul_f32_e32 v10, v0, v10
	v_mul_f32_e32 v18, v226, v22
	v_mul_f32_e32 v10, v227, v10
	v_lshlrev_b32_e32 v23, 16, v11
	v_cvt_pk_bf16_f32 v18, v18, s0
	v_cvt_pk_bf16_f32 v10, v10, s0
	ds_write_b16 v158, v18 offset:2688
	ds_write_b16 v159, v10 offset:2960
	v_mul_f32_e32 v10, v0, v23
	v_mul_f32_e32 v10, v10, v228
	v_and_b32_e32 v11, 0xffff0000, v11
	v_cvt_pk_bf16_f32 v10, v10, s0
	ds_write_b16 v159, v10 offset:3232
	v_mul_f32_e32 v10, v0, v11
	v_mul_f32_e32 v10, v10, v229
	v_lshlrev_b32_e32 v24, 16, v12
	v_cvt_pk_bf16_f32 v10, v10, s0
	ds_write_b16 v159, v10 offset:3504
	v_mul_f32_e32 v10, v0, v24
	v_mul_f32_e32 v10, v10, v222
	v_and_b32_e32 v12, 0xffff0000, v12
	v_cvt_pk_bf16_f32 v10, v10, s0
	ds_write_b16 v159, v10 offset:3776
	v_mul_f32_e32 v10, v0, v12
	v_mul_f32_e32 v10, v10, v223
	v_lshlrev_b32_e32 v25, 16, v13
	v_cvt_pk_bf16_f32 v10, v10, s0
	ds_write_b16 v159, v10 offset:4048
	v_mul_f32_e32 v10, v0, v25
	v_mul_f32_e32 v10, v10, v224
	v_and_b32_e32 v13, 0xffff0000, v13
	v_cvt_pk_bf16_f32 v10, v10, s0
	ds_write_b16 v159, v10 offset:4320
	v_mul_f32_e32 v10, v0, v13
	v_mul_f32_e32 v10, v10, v225
	v_cvt_pk_bf16_f32 v10, v10, s0
	ds_write_b16 v159, v10 offset:4592
	v_lshlrev_b32_e32 v10, 16, v6
	v_and_b32_e32 v22, 0xffff0000, v6
	v_lshlrev_b32_e32 v23, 16, v7
	v_and_b32_e32 v24, 0xffff0000, v7
	v_lshlrev_b32_e32 v25, 16, v8
	v_and_b32_e32 v26, 0xffff0000, v8
	v_lshlrev_b32_e32 v27, 16, v9
	v_and_b32_e32 v28, 0xffff0000, v9
	v_mul_f32_e32 v29, v0, v10
	v_mul_f32_e32 v18, v250, v29
	v_cvt_pk_bf16_f32 v18, v18, s0
	ds_write_b16 v158, v18 offset:4864
	v_mul_f32_e32 v18, v0, v22
	v_mul_f32_e32 v18, v251, v18
	v_cvt_pk_bf16_f32 v18, v18, s0
	ds_write_b16 v159, v18 offset:5136
	v_mul_f32_e32 v18, v0, v23
	v_mul_f32_e32 v18, v18, v252
	v_cvt_pk_bf16_f32 v18, v18, s0
	ds_write_b16 v159, v18 offset:5408
	v_mul_f32_e32 v18, v0, v24
	v_mul_f32_e32 v18, v18, v253
	v_cvt_pk_bf16_f32 v18, v18, s0
	ds_write_b16 v159, v18 offset:5680
	v_mul_f32_e32 v18, v0, v25
	v_mul_f32_e32 v14, v18, v246
	v_cvt_pk_bf16_f32 v14, v14, s0
	ds_write_b16 v159, v14 offset:5952
	v_mul_f32_e32 v14, v0, v26
	v_mul_f32_e32 v14, v14, v247
	v_cvt_pk_bf16_f32 v14, v14, s0
	ds_write_b16 v159, v14 offset:6224
	v_mul_f32_e32 v14, v0, v27
	v_mul_f32_e32 v14, v14, v248
	v_cvt_pk_bf16_f32 v14, v14, s0
	ds_write_b16 v159, v14 offset:6496
	v_mul_f32_e32 v14, v0, v28
	v_mul_f32_e32 v14, v14, v249
	v_cvt_pk_bf16_f32 v14, v14, s0
	ds_write_b16 v159, v14 offset:6768
	v_lshlrev_b32_e32 v14, 16, v2
	v_and_b32_e32 v2, 0xffff0000, v2
; #define MFMA32(a, b, c) __builtin_amdgcn_mfma_f32_32x32x16_bf16((a), (b), (c), 0, 0, 0)
; __device__ __forceinline__ float bf2f(unsigned v) { return __uint_as_float(v << 16); }
; __device__ __forceinline__ u32x4 pack8(f32x4 v0, f32x4 v1) { u32x4 o; o.x = pkbf(v0.x, v0.y); o.y = pkbf(v0.z, v0.w); o.z = pkbf(v1.x, v1.y); o.w = pkbf(v1.z, v1.w); return o; }
; __device__ __forceinline__ void gmlp_unit(const TI ti, CArgs& a, int l, int u, unsigned char* ldsg) {
;     ...
;         f32x16 acc0, acc1;
; #pragma unroll
;         for (int i = 0; i < 16; ++i) { acc0[i] = 0.f; acc1[i] = 0.f; }
;         const float* wrow = wsp + ((size_t)g * 128 + tt * 32 + r) * 128;
; #pragma unroll
;         for (int ks = 0; ks < 8; ++ks) {
;             const f32x4 a0 = *(const f32x4*)(wrow + 16 * ks + 8 * h), a1 = *(const f32x4*)(wrow + 16 * ks + 8 * h + 4);
;             const bf16x8 af = __builtin_bit_cast(bf16x8, pack8(a0, a1));
;             const bf16x8 b0 = *(const bf16x8*)(VNT + (chh * 64 + r) * 136 + 16 * ks + 8 * h);
;             const bf16x8 b1 = *(const bf16x8*)(VNT + (chh * 64 + 32 + r) * 136 + 16 * ks + 8 * h);
;             acc0 = MFMA32(af, b0, acc0); acc1 = MFMA32(af, b1, acc1);
;         }
;         {
;             const bf16_t* GUr = GU; float uu0[16], uu1[16], bb[16];
; #pragma unroll
;             for (int reg = 0; reg < 16; ++reg) {
;                 const int t = tt * 32 + (reg & 3) + 8 * (reg >> 2) + 4 * h; const size_t i0 = (R0 + t) * 1024 + g * 128 + chh * 64 + r;
;                 bb[reg] = bsp[g * 128 + t]; uu0[reg] = bf2f(GUr[i0]); uu1[reg] = bf2f(GUr[i0 + 32]);
	v_mul_f32_e32 v14, v0, v14
	v_mul_f32_e32 v2, v0, v2
	v_mul_f32_e32 v10, v242, v14
	v_mul_f32_e32 v2, v243, v2
	v_lshlrev_b32_e32 v15, 16, v3
	v_cvt_pk_bf16_f32 v10, v10, s0
	v_cvt_pk_bf16_f32 v2, v2, s0
	ds_write_b16 v158, v10 offset:7040
	ds_write_b16 v159, v2 offset:7312
	v_mul_f32_e32 v2, v0, v15
	v_mul_f32_e32 v2, v2, v244
	v_and_b32_e32 v3, 0xffff0000, v3
	v_cvt_pk_bf16_f32 v2, v2, s0
	ds_write_b16 v159, v2 offset:7584
	v_mul_f32_e32 v2, v0, v3
	v_mul_f32_e32 v2, v2, v245
	v_lshlrev_b32_e32 v16, 16, v4
	v_cvt_pk_bf16_f32 v2, v2, s0
	ds_write_b16 v159, v2 offset:7856
	v_mul_f32_e32 v2, v0, v16
	v_mul_f32_e32 v2, v2, v238
	v_and_b32_e32 v4, 0xffff0000, v4
	v_cvt_pk_bf16_f32 v2, v2, s0
	ds_write_b16 v159, v2 offset:8128
	v_mul_f32_e32 v2, v0, v4
	v_mul_f32_e32 v2, v2, v239
	v_lshlrev_b32_e32 v17, 16, v5
	v_and_b32_e32 v5, 0xffff0000, v5
	v_cvt_pk_bf16_f32 v2, v2, s0
	ds_write_b16 v159, v2 offset:8400
	v_mul_f32_e32 v2, v0, v17
	v_mul_f32_e32 v0, v0, v5
	v_mul_f32_e32 v2, v2, v240
	v_mul_f32_e32 v0, v0, v241
	v_cvt_pk_bf16_f32 v2, v2, s0
	v_cvt_pk_bf16_f32 v0, v0, s0
	ds_write_b16 v159, v2 offset:8672
	ds_write_b16 v159, v0 offset:8944
	v_lshl_add_u64 v[28:29], v[128:129], 0, s[42:43]
	v_add_co_u32_e32 v148, vcc, s82, v28
	s_nop 0
	v_addc_co_u32_e32 v149, vcc, 0, v29, vcc
	global_load_ushort v222, v[148:149], off
	global_load_ushort v223, v[148:149], off offset:64
	global_load_ushort v224, v[148:149], off offset:2048
	global_load_ushort v225, v[148:149], off offset:2112
	global_load_ushort v226, v[150:151], off offset:-64
	global_load_ushort v227, v[150:151], off
	global_load_ushort v228, v[150:151], off offset:1984
	global_load_ushort v229, v[150:151], off offset:2048
	v_lshl_add_u64 v[28:29], v[132:133], 0, s[42:43]
	v_add_co_u32_e32 v152, vcc, s82, v28
	v_lshl_add_u64 v[132:133], v[132:133], 0, s[24:25]
	s_nop 0
	v_addc_co_u32_e32 v153, vcc, 0, v29, vcc
	global_load_ushort v230, v[152:153], off
	global_load_ushort v231, v[152:153], off offset:64
	global_load_ushort v232, v[152:153], off offset:2048
	global_load_ushort v233, v[152:153], off offset:2112
	global_load_ushort v234, v[154:155], off offset:-64
	global_load_ushort v235, v[154:155], off
	global_load_ushort v236, v[154:155], off offset:1984
	global_load_ushort v237, v[154:155], off offset:2048
	v_lshl_add_u64 v[28:29], v[136:137], 0, s[42:43]
	v_add_co_u32_e32 v166, vcc, s82, v28
	v_lshl_add_u64 v[136:137], v[136:137], 0, s[24:25]
	s_nop 0
	v_addc_co_u32_e32 v167, vcc, 0, v29, vcc
	global_load_ushort v238, v[166:167], off
	global_load_ushort v239, v[166:167], off offset:64
	global_load_ushort v240, v[166:167], off offset:2048
	global_load_ushort v241, v[166:167], off offset:2112
	v_lshl_add_u64 v[26:27], v[140:141], 0, s[42:43]
	v_add_co_u32_e32 v170, vcc, s82, v26
	v_lshl_add_u64 v[140:141], v[140:141], 0, s[24:25]
	s_nop 0
	v_addc_co_u32_e32 v171, vcc, 0, v27, vcc
	global_load_ushort v242, v[170:171], off
	global_load_ushort v243, v[170:171], off offset:64
	v_lshl_add_u64 v[26:27], v[142:143], 0, s[42:43]
	v_add_co_u32_e32 v182, vcc, s82, v26
	v_lshl_add_u64 v[142:143], v[142:143], 0, s[24:25]
	s_nop 0
	v_addc_co_u32_e32 v183, vcc, 0, v27, vcc
	v_add_co_u32_e32 v184, vcc, s3, v26
	s_nop 1
	v_addc_co_u32_e32 v185, vcc, 0, v27, vcc
	global_load_ushort v244, v[168:169], off offset:-64
	global_load_ushort v245, v[168:169], off
	global_load_ushort v246, v[168:169], off offset:1984
	global_load_ushort v247, v[168:169], off offset:2048
	global_load_ushort v248, v[184:185], off
	global_load_ushort v249, v[184:185], off offset:64
	global_load_ushort v250, v[184:185], off offset:2048
	global_load_ushort v251, v[184:185], off offset:2112
	global_load_ushort v252, v[182:183], off offset:2048
	global_load_ushort v253, v[182:183], off offset:2112
	s_waitcnt lgkmcnt(0)
	s_barrier
	v_cvt_pk_bf16_f32 v18, v90, v91
	v_cvt_pk_bf16_f32 v19, v92, v93
	v_cvt_pk_bf16_f32 v20, v94, v95
	v_cvt_pk_bf16_f32 v21, v96, v97
	v_cvt_pk_bf16_f32 v34, v98, v99
	v_cvt_pk_bf16_f32 v35, v100, v101
	v_cvt_pk_bf16_f32 v36, v162, v163
	v_cvt_pk_bf16_f32 v37, v164, v165
	v_cvt_pk_bf16_f32 v42, v198, v199
	v_cvt_pk_bf16_f32 v43, v200, v201
	v_cvt_pk_bf16_f32 v44, v202, v203
	v_cvt_pk_bf16_f32 v45, v204, v205
	v_cvt_pk_bf16_f32 v50, v206, v207
	v_cvt_pk_bf16_f32 v51, v208, v209
	v_cvt_pk_bf16_f32 v52, v210, v211
	v_cvt_pk_bf16_f32 v53, v212, v213
	global_load_dwordx4 v[90:93], v[144:145], off offset:0
	global_load_dwordx4 v[94:97], v[144:145], off offset:16
	global_load_dwordx4 v[98:101], v[144:145], off offset:64
	global_load_dwordx4 v[162:165], v[144:145], off offset:80
	global_load_dwordx4 v[198:201], v[144:145], off offset:128
	global_load_dwordx4 v[202:205], v[144:145], off offset:144
	global_load_dwordx4 v[206:209], v[144:145], off offset:192
	global_load_dwordx4 v[210:213], v[144:145], off offset:208
	v_lshl_add_u64 v[144:145], v[144:145], 0, s[4:5]
	ds_read_b128 v[26:29], v157 offset:512
	ds_read_b128 v[30:33], v157 offset:544
	ds_read_b128 v[174:177], v157 offset:576
	ds_read_b128 v[214:217], v157 offset:608
	ds_read_b128 v[22:25], v157 offset:9216
	ds_read_b128 v[38:41], v157 offset:9248
	ds_read_b128 v[46:49], v157 offset:9280
	ds_read_b128 v[54:57], v157 offset:9312
	s_waitcnt lgkmcnt(7)
	v_mfma_f32_32x32x16_bf16 v[2:17], v[18:21], v[26:29], 0
	s_waitcnt lgkmcnt(6)
	v_mfma_f32_32x32x16_bf16 v[2:17], v[34:37], v[30:33], v[2:17]
	ds_read_b128 v[26:29], v157 offset:640
	ds_read_b128 v[30:33], v157 offset:672
	s_waitcnt lgkmcnt(7)
	v_mfma_f32_32x32x16_bf16 v[2:17], v[42:45], v[174:177], v[2:17]
	s_waitcnt lgkmcnt(6)
; #define MFMA32(a, b, c) __builtin_amdgcn_mfma_f32_32x32x16_bf16((a), (b), (c), 0, 0, 0)
; __device__ __forceinline__ float bf2f(unsigned v) { return __uint_as_float(v << 16); }
; __device__ __forceinline__ u32x4 pack8(f32x4 v0, f32x4 v1) { u32x4 o; o.x = pkbf(v0.x, v0.y); o.y = pkbf(v0.z, v0.w); o.z = pkbf(v1.x, v1.y); o.w = pkbf(v1.z, v1.w); return o; }
; __device__ __forceinline__ void gmlp_unit(const TI ti, CArgs& a, int l, int u, unsigned char* ldsg) {
;     ...
;         for (int ks = 0; ks < 8; ++ks) {
;             const f32x4 a0 = *(const f32x4*)(wrow + 16 * ks + 8 * h), a1 = *(const f32x4*)(wrow + 16 * ks + 8 * h + 4);
;             const bf16x8 af = __builtin_bit_cast(bf16x8, pack8(a0, a1));
;             const bf16x8 b0 = *(const bf16x8*)(VNT + (chh * 64 + r) * 136 + 16 * ks + 8 * h);
;             const bf16x8 b1 = *(const bf16x8*)(VNT + (chh * 64 + 32 + r) * 136 + 16 * ks + 8 * h);
;             acc0 = MFMA32(af, b0, acc0); acc1 = MFMA32(af, b1, acc1);
;         }
;         {
;             const bf16_t* GUr = GU; float uu0[16], uu1[16], bb[16];
; #pragma unroll
;             for (int reg = 0; reg < 16; ++reg) {
;                 const int t = tt * 32 + (reg & 3) + 8 * (reg >> 2) + 4 * h; const size_t i0 = (R0 + t) * 1024 + g * 128 + chh * 64 + r;
;                 bb[reg] = bsp[g * 128 + t]; uu0[reg] = bf2f(GUr[i0]); uu1[reg] = bf2f(GUr[i0 + 32]);
;             }
;             asm volatile("" ::: "memory");
; #pragma unroll
;             for (int reg = 0; reg < 16; ++reg) {
	v_mfma_f32_32x32x16_bf16 v[2:17], v[50:53], v[214:217], v[2:17]
	ds_read_b128 v[174:177], v157 offset:704
	ds_read_b128 v[214:217], v157 offset:736
	ds_read_b128 v[62:65], v157 offset:9344
	ds_read_b128 v[70:73], v157 offset:9376
	ds_read_b128 v[78:81], v157 offset:9408
	ds_read_b128 v[86:89], v157 offset:9440
	s_waitcnt vmcnt(0)
	v_cvt_pk_bf16_f32 v58, v90, v91
	v_cvt_pk_bf16_f32 v59, v92, v93
	v_cvt_pk_bf16_f32 v60, v94, v95
	v_cvt_pk_bf16_f32 v61, v96, v97
	v_cvt_pk_bf16_f32 v66, v98, v99
	v_cvt_pk_bf16_f32 v67, v100, v101
	v_cvt_pk_bf16_f32 v68, v162, v163
	v_cvt_pk_bf16_f32 v69, v164, v165
	v_cvt_pk_bf16_f32 v74, v198, v199
	v_cvt_pk_bf16_f32 v75, v200, v201
	v_cvt_pk_bf16_f32 v76, v202, v203
	v_cvt_pk_bf16_f32 v77, v204, v205
	v_cvt_pk_bf16_f32 v82, v206, v207
	v_cvt_pk_bf16_f32 v83, v208, v209
	v_cvt_pk_bf16_f32 v84, v210, v211
	v_cvt_pk_bf16_f32 v85, v212, v213
	s_waitcnt lgkmcnt(7)
	v_mfma_f32_32x32x16_bf16 v[2:17], v[58:61], v[26:29], v[2:17]
	s_waitcnt lgkmcnt(6)
	v_mfma_f32_32x32x16_bf16 v[2:17], v[66:69], v[30:33], v[2:17]
	s_waitcnt lgkmcnt(5)
	v_mfma_f32_32x32x16_bf16 v[2:17], v[74:77], v[174:177], v[2:17]
	s_waitcnt lgkmcnt(4)
	v_mfma_f32_32x32x16_bf16 v[2:17], v[82:85], v[214:217], v[2:17]
	s_waitcnt lgkmcnt(0)
	v_lshl_add_u64 v[26:27], v[110:111], 0, s[46:47]
	global_load_dwordx4 v[90:93], v[26:27], off
	global_load_dwordx4 v[94:97], v[26:27], off offset:32
	global_load_dwordx4 v[98:101], v[26:27], off offset:64
	global_load_dwordx4 v[162:165], v[26:27], off offset:96
	v_lshl_add_u64 v[128:129], v[128:129], 0, s[24:25]
	s_add_u32 s46, s46, 0x200
	s_addc_u32 s47, s47, 0
	s_cmpk_lg_i32 s46, 0x1000
	s_waitcnt vmcnt(0)
	v_lshlrev_b32_e32 v0, 16, v222
	v_lshlrev_b32_e32 v161, 16, v223
	v_lshlrev_b32_e32 v174, 16, v224
	v_lshlrev_b32_e32 v175, 16, v225
	v_lshlrev_b32_e32 v176, 16, v226
	v_lshlrev_b32_e32 v177, 16, v227
	v_lshlrev_b32_e32 v179, 16, v228
	v_lshlrev_b32_e32 v181, 16, v229
	v_lshlrev_b32_e32 v197, 16, v230
	v_lshlrev_b32_e32 v198, 16, v231
	v_lshlrev_b32_e32 v199, 16, v232
	v_lshlrev_b32_e32 v200, 16, v233
	v_lshlrev_b32_e32 v201, 16, v234
	v_lshlrev_b32_e32 v202, 16, v235
	v_lshlrev_b32_e32 v203, 16, v236
	v_lshlrev_b32_e32 v204, 16, v237
	v_lshlrev_b32_e32 v205, 16, v238
	v_lshlrev_b32_e32 v206, 16, v239
	v_lshlrev_b32_e32 v207, 16, v240
	v_lshlrev_b32_e32 v208, 16, v241
	v_lshlrev_b32_e32 v209, 16, v244
	v_lshlrev_b32_e32 v210, 16, v245
	v_lshlrev_b32_e32 v211, 16, v246
	v_lshlrev_b32_e32 v212, 16, v247
	v_lshlrev_b32_e32 v213, 16, v242
	v_lshlrev_b32_e32 v214, 16, v243
	v_lshlrev_b32_e32 v215, 16, v252
	v_lshlrev_b32_e32 v216, 16, v253
	v_lshlrev_b32_e32 v217, 16, v248
	v_lshlrev_b32_e32 v218, 16, v249
	v_lshlrev_b32_e32 v219, 16, v250
	v_lshlrev_b32_e32 v220, 16, v251
	v_add_f32_e32 v2, v2, v90
	v_mul_f32_e32 v0, v2, v0
	v_cvt_pk_bf16_f32 v0, v0, s0
	global_store_short v[148:149], v0, off
	v_mfma_f32_32x32x16_bf16 v[18:33], v[18:21], v[22:25], 0
	v_mfma_f32_32x32x16_bf16 v[18:33], v[34:37], v[38:41], v[18:33]
	v_mfma_f32_32x32x16_bf16 v[18:33], v[42:45], v[46:49], v[18:33]
	v_mfma_f32_32x32x16_bf16 v[18:33], v[50:53], v[54:57], v[18:33]
	v_mfma_f32_32x32x16_bf16 v[18:33], v[58:61], v[62:65], v[18:33]
	v_mfma_f32_32x32x16_bf16 v[18:33], v[66:69], v[70:73], v[18:33]
	v_mfma_f32_32x32x16_bf16 v[18:33], v[74:77], v[78:81], v[18:33]
	s_waitcnt lgkmcnt(0)
; __device__ __forceinline__ bf16_t f2bf(float f) { return (bf16_t)(pkbf(f, 0.f) & 0xffffu); }
; __device__ __forceinline__ void gmlp_unit(const TI ti, CArgs& a, int l, int u, unsigned char* ldsg) {
;     ...
;             for (int reg = 0; reg < 16; ++reg) {
;                 const int t = tt * 32 + (reg & 3) + 8 * (reg >> 2) + 4 * h; const size_t i0 = (R0 + t) * 1024 + g * 128 + chh * 64 + r;
;                 GU[i0] = f2bf(uu0[reg] * (acc0[reg] + bb[reg])); GU[i0 + 32] = f2bf(uu1[reg] * (acc1[reg] + bb[reg]));
;             }
;         }
;         __syncthreads();
;     }
	v_mfma_f32_32x32x16_bf16 v[18:33], v[82:85], v[86:89], v[18:33]
	s_nop 11
	v_add_f32_e32 v0, v90, v18
	v_mul_f32_e32 v0, v0, v161
	v_cvt_pk_bf16_f32 v0, v0, s0
	global_store_short v[148:149], v0, off offset:64
	v_add_f32_e32 v0, v3, v91
	v_mul_f32_e32 v0, v0, v174
	v_cvt_pk_bf16_f32 v0, v0, s0
	global_store_short v[148:149], v0, off offset:2048
	v_add_f32_e32 v0, v91, v19
	v_mul_f32_e32 v0, v0, v175
	v_cvt_pk_bf16_f32 v0, v0, s0
	global_store_short v[148:149], v0, off offset:2112
	v_add_f32_e32 v0, v4, v92
	v_mul_f32_e32 v0, v0, v176
	v_cvt_pk_bf16_f32 v0, v0, s0
	global_store_short v[150:151], v0, off offset:-64
	v_add_f32_e32 v0, v92, v20
	v_mul_f32_e32 v0, v0, v177
	v_cvt_pk_bf16_f32 v0, v0, s0
	global_store_short v[150:151], v0, off
	v_add_f32_e32 v0, v5, v93
	v_mul_f32_e32 v0, v0, v179
	v_cvt_pk_bf16_f32 v0, v0, s0
	global_store_short v[150:151], v0, off offset:1984
	v_add_f32_e32 v0, v93, v21
	v_mul_f32_e32 v0, v0, v181
	v_cvt_pk_bf16_f32 v0, v0, s0
	global_store_short v[150:151], v0, off offset:2048
	v_add_f32_e32 v0, v6, v94
	v_mul_f32_e32 v0, v0, v197
	v_cvt_pk_bf16_f32 v0, v0, s0
	global_store_short v[152:153], v0, off
	v_add_f32_e32 v0, v94, v22
	v_mul_f32_e32 v0, v0, v198
	v_cvt_pk_bf16_f32 v0, v0, s0
	global_store_short v[152:153], v0, off offset:64
	v_add_f32_e32 v0, v7, v95
	v_mul_f32_e32 v0, v0, v199
	v_cvt_pk_bf16_f32 v0, v0, s0
	global_store_short v[152:153], v0, off offset:2048
	v_add_f32_e32 v0, v95, v23
	v_mul_f32_e32 v0, v0, v200
	v_cvt_pk_bf16_f32 v0, v0, s0
	global_store_short v[152:153], v0, off offset:2112
	v_add_f32_e32 v0, v8, v96
	v_mul_f32_e32 v0, v0, v201
	v_cvt_pk_bf16_f32 v0, v0, s0
	global_store_short v[154:155], v0, off offset:-64
	v_add_f32_e32 v0, v96, v24
	v_mul_f32_e32 v0, v0, v202
	v_cvt_pk_bf16_f32 v0, v0, s0
	global_store_short v[154:155], v0, off
	v_add_f32_e32 v0, v9, v97
	v_mul_f32_e32 v0, v0, v203
	v_cvt_pk_bf16_f32 v0, v0, s0
	global_store_short v[154:155], v0, off offset:1984
	v_add_f32_e32 v0, v97, v25
	v_mul_f32_e32 v0, v0, v204
	v_cvt_pk_bf16_f32 v0, v0, s0
	global_store_short v[154:155], v0, off offset:2048
	v_add_f32_e32 v0, v10, v98
	v_mul_f32_e32 v0, v0, v205
	v_cvt_pk_bf16_f32 v0, v0, s0
	global_store_short v[166:167], v0, off
	v_add_f32_e32 v0, v98, v26
	v_mul_f32_e32 v0, v0, v206
	v_cvt_pk_bf16_f32 v0, v0, s0
	global_store_short v[166:167], v0, off offset:64
	v_add_f32_e32 v0, v11, v99
	v_mul_f32_e32 v0, v0, v207
	v_cvt_pk_bf16_f32 v0, v0, s0
	global_store_short v[166:167], v0, off offset:2048
	v_add_f32_e32 v0, v99, v27
	v_mul_f32_e32 v0, v0, v208
	v_cvt_pk_bf16_f32 v0, v0, s0
	global_store_short v[166:167], v0, off offset:2112
	v_add_f32_e32 v0, v12, v100
	v_mul_f32_e32 v0, v0, v209
	v_cvt_pk_bf16_f32 v0, v0, s0
	global_store_short v[168:169], v0, off offset:-64
	v_add_f32_e32 v0, v100, v28
	v_mul_f32_e32 v0, v0, v210
	v_cvt_pk_bf16_f32 v0, v0, s0
	global_store_short v[168:169], v0, off
	v_add_f32_e32 v0, v13, v101
	v_mul_f32_e32 v0, v0, v211
	v_cvt_pk_bf16_f32 v0, v0, s0
	global_store_short v[168:169], v0, off offset:1984
	v_add_f32_e32 v0, v101, v29
	v_mul_f32_e32 v0, v0, v212
	v_cvt_pk_bf16_f32 v0, v0, s0
	global_store_short v[168:169], v0, off offset:2048
	v_add_f32_e32 v0, v14, v162
	v_mul_f32_e32 v0, v0, v213
	v_cvt_pk_bf16_f32 v0, v0, s0
	global_store_short v[170:171], v0, off
	v_add_f32_e32 v0, v162, v30
	v_mul_f32_e32 v0, v0, v214
	v_cvt_pk_bf16_f32 v0, v0, s0
	global_store_short v[170:171], v0, off offset:64
	v_add_f32_e32 v0, v15, v163
	v_mul_f32_e32 v0, v0, v215
	v_cvt_pk_bf16_f32 v0, v0, s0
	global_store_short v[182:183], v0, off offset:2048
	v_add_f32_e32 v0, v163, v31
	v_mul_f32_e32 v0, v0, v216
	v_cvt_pk_bf16_f32 v0, v0, s0
	global_store_short v[182:183], v0, off offset:2112
	v_add_f32_e32 v0, v16, v164
	v_mul_f32_e32 v0, v0, v217
	v_cvt_pk_bf16_f32 v0, v0, s0
	global_store_short v[184:185], v0, off
	v_add_f32_e32 v0, v164, v32
	v_mul_f32_e32 v0, v0, v218
	v_cvt_pk_bf16_f32 v0, v0, s0
	global_store_short v[184:185], v0, off offset:64
	v_add_f32_e32 v0, v17, v165
	v_mul_f32_e32 v0, v0, v219
	v_cvt_pk_bf16_f32 v0, v0, s0
	global_store_short v[184:185], v0, off offset:2048
	v_add_f32_e32 v0, v165, v33
	v_mul_f32_e32 v0, v0, v220
	v_cvt_pk_bf16_f32 v0, v0, s0
	global_store_short v[184:185], v0, off offset:2112
	s_barrier
	s_cbranch_scc1 .LBB0_447
	s_add_i32 s1, s1, s0
	v_lshl_add_u64 v[104:105], v[104:105], 0, s[44:45]
	v_lshl_add_u64 v[106:107], v[106:107], 0, s[44:45]
	v_lshl_add_u64 v[112:113], v[112:113], 0, s[44:45]
	v_lshl_add_u64 v[114:115], v[114:115], 0, s[44:45]
	v_lshl_add_u64 v[116:117], v[116:117], 0, s[44:45]
	v_lshl_add_u64 v[118:119], v[118:119], 0, s[44:45]
	v_lshl_add_u64 v[120:121], v[120:121], 0, s[44:45]
	v_lshl_add_u64 v[122:123], v[122:123], 0, s[44:45]
	v_lshl_add_u64 v[124:125], v[124:125], 0, s[44:45]
	s_cmp_ge_i32 s1, s10
	v_lshl_add_u64 v[126:127], v[126:127], 0, s[44:45]
	s_cbranch_scc0 .LBB0_436
